# diff attention: next unit's first two K/V tiles prefetched by the last two loop iterations (replaces redundant tile reloads and the post-loop prefetch)
# speedup vs baseline: 1.0034x; 1.0034x over previous
; __device__ __forceinline__ s16x4 vtr(const ALDS unsigned char* p) { return __builtin_bit_cast(s16x4, __builtin_amdgcn_ds_read_tr16_b64_v4i16((ALDS s16x4*)p)); }
; template <int DV, bool BAND> ...
;     ...
;         float ssum = 0.f;
;         bf16x8 pfs[4];
;     ...
;         ATT_EXP_SLICE(p0, 0, pfs[0]);
; #pragma unroll
;         for (int ks = 0; ks < 4; ++ks) {
;             if (ks + 1 < 4) {
; #pragma unroll
;                 for (int db = 0; db < NDB; ++db) { vlo[(ks + 1) & 1][db] = vtr(sb + va[db] + (ks + 1) * (16 * ROWB)); vhh[(ks + 1) & 1][db] = vtr(sb + va[db] + (ks + 1) * (16 * ROWB) + 4 * ROWB); }
;             }
; #pragma unroll
;             for (int db = 0; db < NDB; ++db) {
;                 const s16x4 lo = vlo[ks & 1][db], hh = vhh[ks & 1][db];
;                 const bf16x8 vf = (bf16x8){lo[0], lo[1], lo[2], lo[3], hh[0], hh[1], hh[2], hh[3]};
;                 o[db] = __builtin_amdgcn_mfma_f32_32x32x16_bf16(vf, pfs[ks], o[db], 0, 0, 0);
;             }
;             if (ks == 0) ATT_EXP_SLICE(p0, 8, pfs[1]);
;             if (ks == 1) ATT_EXP_SLICE(p1, 0, pfs[2]);
;             if (ks == 2) ATT_EXP_SLICE(p1, 8, pfs[3]);
;         }
;     ...
;         l += ssum;
;         s_cur = (s_cur == 2 * SLOT) ? 0 : s_cur + SLOT; s_n2 = (s_n2 == 2 * SLOT) ? 0 : s_n2 + SLOT;
;     }
.LBB0_774:
	v_exp_f32_e32 v167, v98
	v_exp_f32_e32 v169, v99
	v_exp_f32_e32 v171, v100
	v_exp_f32_e32 v173, v101
	v_exp_f32_e32 v166, v102
	v_exp_f32_e32 v168, v103
	v_exp_f32_e32 v170, v104
	v_exp_f32_e32 v172, v105
	v_cvt_pk_bf16_f32 v98, v167, v169
	v_cvt_pk_bf16_f32 v99, v171, v173
	v_cvt_pk_bf16_f32 v100, v166, v168
	v_cvt_pk_bf16_f32 v101, v170, v172
	ds_read_b64_tr_b16 v[102:103], v164 offset:20480
	ds_read_b64_tr_b16 v[104:105], v164 offset:21504
	s_cmp_eq_u32 s4, 63
	s_cbranch_scc1 .Ldiff_b2_nowait
	s_waitcnt vmcnt(4)
.Ldiff_b2_nowait:
	s_barrier
	s_setprio 0
	s_waitcnt lgkmcnt(8)
	v_mfma_f32_32x32x16_bf16 v[50:65], v[142:145], v[98:101], v[50:65]
	v_exp_f32_e32 v142, v82
	v_exp_f32_e32 v143, v83
	v_exp_f32_e32 v144, v84
	v_exp_f32_e32 v145, v85
	v_exp_f32_e32 v165, v86
	v_exp_f32_e32 v174, v87
	v_exp_f32_e32 v175, v88
	s_waitcnt lgkmcnt(6)
	v_mfma_f32_32x32x16_bf16 v[34:49], v[138:141], v[98:101], v[34:49]
	v_exp_f32_e32 v139, v110
	v_exp_f32_e32 v141, v111
	v_exp_f32_e32 v138, v112
	v_exp_f32_e32 v140, v113
	v_exp_f32_e32 v176, v89
	v_cvt_pk_bf16_f32 v86, v142, v143
	v_cvt_pk_bf16_f32 v87, v144, v145
	s_waitcnt lgkmcnt(4)
	v_mfma_f32_32x32x16_bf16 v[18:33], v[134:137], v[98:101], v[18:33]
	v_exp_f32_e32 v135, v106
	v_exp_f32_e32 v137, v107
	v_exp_f32_e32 v134, v108
	v_exp_f32_e32 v136, v109
	ds_read_b64_tr_b16 v[106:107], v164 offset:24576
	ds_read_b64_tr_b16 v[108:109], v164 offset:25600
	v_cvt_pk_bf16_f32 v88, v165, v174
	v_cvt_pk_bf16_f32 v89, v175, v176
	s_waitcnt lgkmcnt(4)
	v_mfma_f32_32x32x16_bf16 v[2:17], v[130:133], v[98:101], v[2:17]
	v_cvt_pk_bf16_f32 v98, v135, v137
	v_cvt_pk_bf16_f32 v99, v134, v136
	v_cvt_pk_bf16_f32 v100, v139, v141
	v_cvt_pk_bf16_f32 v101, v138, v140
	v_add_f32_e64 v82, v168, v166
	v_add_f32_e64 v83, v169, v167
	v_exp_f32_e32 v0, v90
	v_exp_f32_e32 v90, v94
	s_waitcnt lgkmcnt(2)
	v_mfma_f32_32x32x16_bf16 v[50:65], v[102:105], v[98:101], v[50:65]
	ds_read_b64_tr_b16 v[102:103], v163 offset:4096
	ds_read_b64_tr_b16 v[104:105], v163 offset:5120
	ds_read_b64_tr_b16 v[110:111], v164 offset:29696
	v_exp_f32_e32 v94, v96
	v_exp_f32_e32 v96, v97
	v_add_f32_e32 v97, v176, v175
	s_add_i32 s7, s6, 0x8000
	s_cmp_lg_u32 s6, 0x18000
	s_cselect_b32 s6, s7, 0
	s_waitcnt lgkmcnt(1)
	v_mfma_f32_32x32x16_bf16 v[34:49], v[102:105], v[98:101], v[34:49]
	ds_read_b64_tr_b16 v[102:103], v161 offset:4096
	ds_read_b64_tr_b16 v[104:105], v161 offset:5120
	ds_read_b64_tr_b16 v[130:131], v161 offset:8192
	ds_read_b64_tr_b16 v[132:133], v161 offset:9216
	s_add_i32 s7, s5, 0x8000
	s_cmp_lg_u32 s5, 0x18000
	s_cselect_b32 s5, s7, 0
	s_add_i32 s4, s4, 1
	s_cmp_lg_u32 s4, 64
	s_waitcnt lgkmcnt(2)
	v_mfma_f32_32x32x16_bf16 v[18:33], v[102:105], v[98:101], v[18:33]
	ds_read_b64_tr_b16 v[102:103], v162 offset:4096
	ds_read_b64_tr_b16 v[104:105], v162 offset:5120
	ds_read_b64_tr_b16 v[84:85], v161 offset:13312
	s_waitcnt lgkmcnt(1)
	v_mfma_f32_32x32x16_bf16 v[2:17], v[102:105], v[98:101], v[2:17]
	v_add_f32_e64 v102, v172, v170
	v_add_f32_e64 v103, v173, v171
	v_add_f32_e64 v82, v102, v82
	v_add_f32_e64 v83, v103, v83
	v_mfma_f32_32x32x16_bf16 v[50:65], v[106:109], v[86:89], v[50:65]
	ds_read_b64_tr_b16 v[98:99], v163 offset:8192
	ds_read_b64_tr_b16 v[100:101], v163 offset:9216
	ds_read_b64_tr_b16 v[108:109], v164 offset:28672
	ds_read_b64_tr_b16 v[102:103], v163 offset:12288
	ds_read_b64_tr_b16 v[104:105], v163 offset:13312
	v_pk_add_f32 v[106:107], v[82:83], v[82:83] op_sel_hi:[0,1]
	v_pk_add_f32 v[82:83], v[136:137], v[134:135]
	v_exp_f32_e32 v106, v91
	v_pk_add_f32 v[112:113], v[82:83], v[82:83] op_sel_hi:[0,1]
	v_pk_add_f32 v[82:83], v[140:141], v[138:139]
	s_waitcnt lgkmcnt(3)
	v_mfma_f32_32x32x16_bf16 v[34:49], v[98:101], v[86:89], v[34:49]
	ds_read_b64_tr_b16 v[98:99], v162 offset:8192
	ds_read_b64_tr_b16 v[100:101], v162 offset:9216
	v_add_f32_e64 v134, v82, v82
	v_add_f32_e64 v135, v82, v83
	v_exp_f32_e32 v112, v92
	v_exp_f32_e32 v134, v93
	v_exp_f32_e32 v92, v95
	v_add_f32_e32 v91, v143, v142
	v_add_f32_e32 v93, v145, v144
	v_mfma_f32_32x32x16_bf16 v[18:33], v[130:133], v[86:89], v[18:33]
	ds_read_b64_tr_b16 v[130:131], v162 offset:12288
	ds_read_b64_tr_b16 v[132:133], v162 offset:13312
	ds_read_b64_tr_b16 v[82:83], v161 offset:12288
	v_add_f32_e32 v95, v174, v165
	s_waitcnt lgkmcnt(3)
	v_mfma_f32_32x32x16_bf16 v[2:17], v[98:101], v[86:89], v[2:17]
	v_cvt_pk_bf16_f32 v86, v0, v106
	v_cvt_pk_bf16_f32 v87, v112, v134
	v_cvt_pk_bf16_f32 v88, v90, v92
	v_cvt_pk_bf16_f32 v89, v94, v96
	v_add_f32_e64 v98, v106, v0
	v_add_f32_e64 v99, v107, v1
	v_pk_add_f32 v[100:101], v[134:135], v[112:113]
	v_pk_add_f32 v[90:91], v[92:93], v[90:91]
	v_mfma_f32_32x32x16_bf16 v[50:65], v[108:111], v[86:89], v[50:65]
	v_add_f32_e64 v92, v96, v94
	v_add_f32_e64 v93, v97, v95
	v_add_f32_e64 v98, v100, v98
	v_add_f32_e64 v99, v101, v99
	v_add_f32_e64 v90, v92, v90
	v_add_f32_e64 v91, v93, v91
	v_pk_add_f32 v[90:91], v[90:91], v[98:99]
	s_nop 0
	v_add_f32_e32 v0, v90, v91
	v_mfma_f32_32x32x16_bf16 v[34:49], v[102:105], v[86:89], v[34:49]
	v_add_f32_e32 v160, v160, v0
	s_waitcnt lgkmcnt(0)
	v_mfma_f32_32x32x16_bf16 v[18:33], v[82:85], v[86:89], v[18:33]
	v_mfma_f32_32x32x16_bf16 v[2:17], v[130:133], v[86:89], v[2:17]
	s_cbranch_scc0 .LBB0_777
; #define ALDS __attribute__((address_space(3)))
; __device__ __forceinline__ s16x4 vtr(const ALDS unsigned char* p) { return __builtin_bit_cast(s16x4, __builtin_amdgcn_ds_read_tr16_b64_v4i16((ALDS s16x4*)p)); }
; template <int DV, bool BAND> ...
;     ...
;     for (int t = t0; t < t1; ++t) {
;         asm volatile("s_waitcnt vmcnt(%0)" :: "n"(NP) : "memory");
;         asm volatile("s_waitcnt lgkmcnt(0)\n\ts_barrier" ::: "memory");
;         const int tn = (t + 2 < t1) ? t + 2 : t1 - 1;
;         const ALDS unsigned char* sb = ring + s_cur;
;         f32x16 p0 = negm, p1 = negm;
;         bf16x8 kf[8];
; #pragma unroll
;         for (int d0 = 0; d0 < 4; ++d0) { kf[2 * d0] = *(const ALDS bf16x8*)(sb + ka + d0 * 2048); kf[2 * d0 + 1] = *(const ALDS bf16x8*)(sb + ka + d0 * 2048 + 512); }
;         s16x4 vlo[2][NDB], vhh[2][NDB];
; #pragma unroll
;         for (int db = 0; db < NDB; ++db) { vlo[0][db] = vtr(sb + va[db]); vhh[0][db] = vtr(sb + va[db] + 4 * ROWB); }
; #pragma unroll
;         for (int d0 = 0; d0 < 4; ++d0) {
;             p0 = __builtin_amdgcn_mfma_f32_32x32x16_bf16(kf[2 * d0], qr[d0], p0, 0, 0, 0);
;             p1 = __builtin_amdgcn_mfma_f32_32x32x16_bf16(kf[2 * d0 + 1], qr[d0], p1, 0, 0, 0);
;         }
;         __builtin_amdgcn_sched_barrier(0);
;         ATT_PIECE(0, tn, s_n2); ATT_PIECE(1, tn, s_n2); ATT_PIECE(2, tn, s_n2); ATT_PIECE(3, tn, s_n2);
.LBB0_775:
	s_add_i32 s7, s6, 0
	s_waitcnt vmcnt(4)
	s_add_i32 s8, s7, s67
	s_waitcnt lgkmcnt(0)
	s_barrier
	s_setprio 1
	v_add3_u32 v0, s8, v153, v154
	ds_read_b128 v[82:85], v0
	ds_read_b128 v[130:133], v0 offset:512
	v_add_u32_e32 v164, s7, v155
	s_waitcnt lgkmcnt(1)
	v_mfma_f32_32x32x16_bf16 v[98:113], v[82:85], v[114:117], v[66:81]
	v_add_u32_e32 v161, s7, v157
	v_add_u32_e32 v163, s7, v156
	s_waitcnt lgkmcnt(0)
	v_mfma_f32_32x32x16_bf16 v[82:97], v[130:133], v[114:117], v[66:81]
	ds_read_b128 v[130:133], v0 offset:2048
	ds_read_b128 v[134:137], v0 offset:2560
	v_add_u32_e32 v162, s7, v158
	s_min_u32 s7, s4, 61
	s_waitcnt lgkmcnt(1)
	v_mfma_f32_32x32x16_bf16 v[98:113], v[130:133], v[118:121], v[98:113]
	s_waitcnt lgkmcnt(0)
	v_mfma_f32_32x32x16_bf16 v[82:97], v[134:137], v[118:121], v[82:97]
	ds_read_b128 v[130:133], v0 offset:4096
	ds_read_b128 v[134:137], v0 offset:4608
	ds_read_b128 v[166:169], v0 offset:6656
	s_waitcnt lgkmcnt(2)
	v_mfma_f32_32x32x16_bf16 v[98:113], v[130:133], v[122:125], v[98:113]
	ds_read_b128 v[130:133], v0 offset:6144
	ds_read_b64_tr_b16 v[142:143], v164 offset:16384
	ds_read_b64_tr_b16 v[144:145], v164 offset:17408
	ds_read_b64_tr_b16 v[138:139], v163
	ds_read_b64_tr_b16 v[140:141], v163 offset:1024
	s_waitcnt lgkmcnt(6)
	v_mfma_f32_32x32x16_bf16 v[82:97], v[134:137], v[122:125], v[82:97]
	s_waitcnt lgkmcnt(4)
	v_mfma_f32_32x32x16_bf16 v[98:113], v[130:133], v[126:129], v[98:113]
	ds_read_b64_tr_b16 v[134:135], v161
	ds_read_b64_tr_b16 v[136:137], v161 offset:1024
	ds_read_b64_tr_b16 v[130:131], v162
	ds_read_b64_tr_b16 v[132:133], v162 offset:1024
	v_mfma_f32_32x32x16_bf16 v[82:97], v[166:169], v[126:129], v[82:97]
	s_cmp_gt_u32 s4, 61
	s_cbranch_scc1 .Ldiff_pf_next
	s_mul_i32 s7, s7, 0x48000
	s_add_u32 s7, s90, s7
	s_addc_u32 s12, s91, 0
; template <int DV, bool BAND> ...
;     ...
;         ATT_PIECE(0, tn, s_n2); ATT_PIECE(1, tn, s_n2); ATT_PIECE(2, tn, s_n2); ATT_PIECE(3, tn, s_n2);
;         __builtin_amdgcn_sched_barrier(0);
;         if (BAND) {
;             if (t == tq - 2 || t == tq + 2) {
;                 const int rel0 = t * 64 + 8 * hi - qpos;
; #pragma unroll
;                 for (int r = 0; r < 16; ++r) { const int rel = rel0 + 16 * (r >> 3) + (r & 7);
;                     if (rel < -128 || rel > 128) p0[r] = -INFINITY;
;                     if (rel + 32 < -128 || rel + 32 > 128) p1[r] = -INFINITY; }
;             }
;         }
;         float mx = fmaxf(p0[0], p1[0]);
; #pragma unroll
;         for (int r = 1; r < 16; ++r) mx = fmaxf(fmaxf(mx, p0[r]), p1[r]);
;         mx = halfswap_max(mx);
;         const bool first = (!BAND) && (t == t0);
;         const float dl = first ? mx : ((mx > THR) ? mx : 0.f);
;         if (__any(dl != 0.f)) {
;             m += dl;
; #pragma unroll
;             for (int r = 0; r < 16; ++r) { p0[r] -= dl; p1[r] -= dl; negm[r] = -m; }
;             const float f = first ? 1.f : __builtin_amdgcn_exp2f(-dl);
;             l *= f;
; #pragma unroll
;             for (int db = 0; db < NDB; ++db)
; #pragma unroll
;                 for (int r = 0; r < 16; ++r) o[db][r] *= f;
;         }
; __device__ __forceinline__ void diff_prefetch(ALDS unsigned char* ring, const int wid, int lane, const bf16_t* qkv, const int u) {
;     ...
;     const int bh = u >> 5, b = bh >> 2, h = bh & 3; const size_t rowbase = (size_t)b * 4096;
;     const char* gb = (const char*)(qkv + rowbase * PITCH);
;     const unsigned koffb = (unsigned)((pi23(lane) * PITCH + 512 + h * 128 + wid * 8) * 2);
;     const unsigned voffb = (unsigned)(((8 * wid + (lane >> 4)) * PITCH + 1024 + h * 128 + (((lane & 15) ^ ((lane >> 4) << 2)) * 8)) * 2);
;     const unsigned ring_a = (unsigned)(uintptr_t)ring;
; #pragma unroll
;     for (int tt = 0; tt < 2; ++tt) { const char* sb_ = gb + (size_t)tt * (64 * PITCH * 2); const unsigned so = (unsigned)tt * 32768u, d = ring_a + so + (unsigned)wid * 1024u;
;         glds16s(koffb, sb_, d); glds16s(koffb, sb_ + 128, d + 8192u);
;         glds16s(voffb, sb_, ring_a + so + 16384u + (unsigned)wid * 2048u); glds16s(voffb, sb_ + 4 * PITCH * 2, ring_a + so + 16384u + (unsigned)wid * 2048u + 1024u); }
.Ldiff_pf_join:
	s_add_u32 s8, s7, 0x90000
	s_addc_u32 s9, s12, 0
	s_add_i32 s13, s5, s30
	s_mov_b32 s10, m0
	s_mov_b32 m0, s13
	s_nop 0
	global_load_lds_dwordx4 v151, s[8:9]
	s_mov_b32 m0, s10
	s_add_u32 s10, s7, 0x90080
	s_addc_u32 s11, s12, 0
	s_addk_i32 s13, 0x2000
	s_mov_b32 s14, m0
	s_mov_b32 m0, s13
	s_nop 0
	global_load_lds_dwordx4 v151, s[10:11]
	s_mov_b32 m0, s14
	s_add_i32 s10, s5, s84
	s_mov_b32 s11, m0
	s_mov_b32 m0, s10
	s_nop 0
	global_load_lds_dwordx4 v152, s[8:9]
	s_mov_b32 m0, s11
	s_add_u32 s8, s7, 0x94800
	s_addc_u32 s9, s12, 0
	s_addk_i32 s10, 0x400
	s_mov_b32 s7, m0
	s_mov_b32 m0, s10
	s_nop 0
	global_load_lds_dwordx4 v152, s[8:9]
	s_mov_b32 m0, s7
	v_max_f32_e32 v0, v82, v82
	v_max_f32_e32 v165, v98, v98
	v_max_f32_e32 v0, v165, v0
	v_max3_f32 v0, v0, v99, v83
	v_max3_f32 v0, v0, v100, v84
	v_max3_f32 v0, v0, v101, v85
	v_max3_f32 v0, v0, v102, v86
	v_max3_f32 v0, v0, v103, v87
	v_max3_f32 v0, v0, v104, v88
	v_max3_f32 v0, v0, v105, v89
	v_max3_f32 v0, v0, v106, v90
	v_max3_f32 v0, v0, v107, v91
	v_max3_f32 v0, v0, v108, v92
	v_max3_f32 v0, v0, v109, v93
	v_max3_f32 v0, v0, v110, v94
	v_max3_f32 v0, v0, v111, v95
	v_max3_f32 v0, v0, v112, v96
	v_max3_f32 v0, v0, v113, v97
	v_mov_b32_e32 v165, v0
	s_nop 1
	v_permlane32_swap_b32_e32 v0, v165
	v_max_f32_e32 v165, v165, v165
	v_max_f32_e32 v0, v0, v0
	v_max_f32_e32 v0, v0, v165
	v_cmp_lt_f32_e32 vcc, s31, v0
	s_cbranch_vccz .LBB0_774
	s_nop 1
	v_cndmask_b32_e32 v0, 0, v0, vcc
	s_nop 0
	v_exp_f32_e64 v68, -v0
	v_add_f32_e32 v159, v159, v0
	v_xor_b32_e32 v66, 0x80000000, v159
	v_pk_add_f32 v[98:99], v[98:99], v[0:1] op_sel_hi:[1,0] neg_lo:[0,1] neg_hi:[0,1]
	v_pk_add_f32 v[82:83], v[82:83], v[0:1] op_sel_hi:[1,0] neg_lo:[0,1] neg_hi:[0,1]
	v_pk_add_f32 v[100:101], v[100:101], v[0:1] op_sel_hi:[1,0] neg_lo:[0,1] neg_hi:[0,1]
	v_pk_add_f32 v[84:85], v[84:85], v[0:1] op_sel_hi:[1,0] neg_lo:[0,1] neg_hi:[0,1]
	v_pk_add_f32 v[102:103], v[102:103], v[0:1] op_sel_hi:[1,0] neg_lo:[0,1] neg_hi:[0,1]
	v_pk_add_f32 v[86:87], v[86:87], v[0:1] op_sel_hi:[1,0] neg_lo:[0,1] neg_hi:[0,1]
	v_pk_add_f32 v[104:105], v[104:105], v[0:1] op_sel_hi:[1,0] neg_lo:[0,1] neg_hi:[0,1]
	v_pk_add_f32 v[88:89], v[88:89], v[0:1] op_sel_hi:[1,0] neg_lo:[0,1] neg_hi:[0,1]
	v_pk_add_f32 v[106:107], v[106:107], v[0:1] op_sel_hi:[1,0] neg_lo:[0,1] neg_hi:[0,1]
	v_pk_add_f32 v[90:91], v[90:91], v[0:1] op_sel_hi:[1,0] neg_lo:[0,1] neg_hi:[0,1]
	v_pk_add_f32 v[108:109], v[108:109], v[0:1] op_sel_hi:[1,0] neg_lo:[0,1] neg_hi:[0,1]
	v_pk_add_f32 v[92:93], v[92:93], v[0:1] op_sel_hi:[1,0] neg_lo:[0,1] neg_hi:[0,1]
	v_pk_add_f32 v[110:111], v[110:111], v[0:1] op_sel_hi:[1,0] neg_lo:[0,1] neg_hi:[0,1]
	v_pk_add_f32 v[94:95], v[94:95], v[0:1] op_sel_hi:[1,0] neg_lo:[0,1] neg_hi:[0,1]
	v_pk_add_f32 v[112:113], v[112:113], v[0:1] op_sel_hi:[1,0] neg_lo:[0,1] neg_hi:[0,1]
	v_pk_add_f32 v[96:97], v[96:97], v[0:1] op_sel_hi:[1,0] neg_lo:[0,1] neg_hi:[0,1]
	v_pk_mul_f32 v[64:65], v[64:65], v[68:69] op_sel_hi:[1,0]
	v_pk_mul_f32 v[62:63], v[62:63], v[68:69] op_sel_hi:[1,0]
	v_pk_mul_f32 v[60:61], v[60:61], v[68:69] op_sel_hi:[1,0]
	v_pk_mul_f32 v[58:59], v[58:59], v[68:69] op_sel_hi:[1,0]
	v_pk_mul_f32 v[56:57], v[56:57], v[68:69] op_sel_hi:[1,0]
	v_pk_mul_f32 v[54:55], v[54:55], v[68:69] op_sel_hi:[1,0]
	v_pk_mul_f32 v[52:53], v[52:53], v[68:69] op_sel_hi:[1,0]
	v_pk_mul_f32 v[50:51], v[50:51], v[68:69] op_sel_hi:[1,0]
	v_pk_mul_f32 v[48:49], v[48:49], v[68:69] op_sel_hi:[1,0]
	v_pk_mul_f32 v[46:47], v[46:47], v[68:69] op_sel_hi:[1,0]
	v_pk_mul_f32 v[44:45], v[44:45], v[68:69] op_sel_hi:[1,0]
	v_pk_mul_f32 v[42:43], v[42:43], v[68:69] op_sel_hi:[1,0]
	v_pk_mul_f32 v[40:41], v[40:41], v[68:69] op_sel_hi:[1,0]
	v_pk_mul_f32 v[38:39], v[38:39], v[68:69] op_sel_hi:[1,0]
	v_pk_mul_f32 v[36:37], v[36:37], v[68:69] op_sel_hi:[1,0]
	v_pk_mul_f32 v[34:35], v[34:35], v[68:69] op_sel_hi:[1,0]
	v_pk_mul_f32 v[32:33], v[32:33], v[68:69] op_sel_hi:[1,0]
	v_pk_mul_f32 v[30:31], v[30:31], v[68:69] op_sel_hi:[1,0]
	v_pk_mul_f32 v[28:29], v[28:29], v[68:69] op_sel_hi:[1,0]
	v_pk_mul_f32 v[26:27], v[26:27], v[68:69] op_sel_hi:[1,0]
	v_pk_mul_f32 v[24:25], v[24:25], v[68:69] op_sel_hi:[1,0]
	v_pk_mul_f32 v[22:23], v[22:23], v[68:69] op_sel_hi:[1,0]
	v_pk_mul_f32 v[20:21], v[20:21], v[68:69] op_sel_hi:[1,0]
	v_pk_mul_f32 v[18:19], v[18:19], v[68:69] op_sel_hi:[1,0]
	v_pk_mul_f32 v[16:17], v[16:17], v[68:69] op_sel_hi:[1,0]
	v_pk_mul_f32 v[14:15], v[14:15], v[68:69] op_sel_hi:[1,0]
	v_pk_mul_f32 v[12:13], v[12:13], v[68:69] op_sel_hi:[1,0]
	v_pk_mul_f32 v[10:11], v[10:11], v[68:69] op_sel_hi:[1,0]
	v_pk_mul_f32 v[8:9], v[8:9], v[68:69] op_sel_hi:[1,0]
	v_pk_mul_f32 v[6:7], v[6:7], v[68:69] op_sel_hi:[1,0]
	v_pk_mul_f32 v[4:5], v[4:5], v[68:69] op_sel_hi:[1,0]
	v_pk_mul_f32 v[2:3], v[2:3], v[68:69] op_sel_hi:[1,0]
	v_mul_f32_e32 v160, v160, v68
	v_mov_b32_e32 v67, v66
	v_mov_b32_e32 v68, v66
	v_mov_b32_e32 v69, v66
	v_mov_b32_e32 v70, v66
	v_mov_b32_e32 v71, v66
	v_mov_b32_e32 v72, v66
	v_mov_b32_e32 v73, v66
	v_mov_b32_e32 v74, v66
	v_mov_b32_e32 v75, v66
	v_mov_b32_e32 v76, v66
	v_mov_b32_e32 v77, v66
	v_mov_b32_e32 v78, v66
	v_mov_b32_e32 v79, v66
	v_mov_b32_e32 v80, v66
	v_mov_b32_e32 v81, v66
	s_branch .LBB0_774
.Ldiff_pf_next:
	v_readlane_b32 s8, v253, 0
	s_add_i32 s8, s0, s8
	s_cmpk_gt_i32 s8, 0x7ff
	s_cbranch_scc1 .Ldiff_pf_red
	s_ashr_i32 s9, s8, 7
	s_mul_hi_i32 s12, s9, 0x1200000
	s_mul_i32 s7, s9, 0x1200000
	s_add_u32 s7, s94, s7
	s_addc_u32 s12, s95, s12
	s_lshr_b32 s9, s8, 5
	s_and_b32 s9, s9, 3
	s_lshr_b32 s10, s0, 5
	s_and_b32 s10, s10, 3
	s_sub_i32 s9, s9, s10
	s_lshl_b32 s9, s9, 8
	s_ashr_i32 s10, s9, 31
	s_add_u32 s7, s7, s9
	s_addc_u32 s12, s12, s10
	s_sub_i32 s9, s4, 62
	s_mul_i32 s9, s9, 0x48000
	s_sub_i32 s9, s9, 0x90000
	s_ashr_i32 s10, s9, 31
	s_add_u32 s7, s7, s9
	s_addc_u32 s12, s12, s10
	s_branch .Ldiff_pf_join
.Ldiff_pf_red:
	s_mul_i32 s7, s7, 0x48000
	s_add_u32 s7, s90, s7
	s_addc_u32 s12, s91, 0
	s_branch .Ldiff_pf_join

; template <int DV, bool BAND> ...
;     ...
;     __builtin_amdgcn_s_setprio(0);
;     asm volatile("s_waitcnt vmcnt(0) lgkmcnt(0)\n\ts_barrier" ::: "memory");
; __device__ __forceinline__ void diff_unit(ALDS unsigned char* ring, const int wid, int lane, const bf16_t* qkv, bf16_t* ymix, const int u, const float lam, const float post, const float* subg, const bool pre, const int u_next) {
;     ...
;     if (u_next >= 0) diff_prefetch(ring, wid, lane, qkv, u_next);
.Ldiff_stag_out:
	v_readlane_b32 s4, v253, 0
	s_add_i32 s0, s0, s4
	s_cmpk_gt_i32 s0, 0x7ff
	s_cselect_b64 s[50:51], -1, 0
	s_cmpk_lt_i32 s0, 0x800
	s_cselect_b32 s4, s0, -1
	v_readlane_b32 s5, v253, 1
	s_setprio 0
	s_cmp_lt_i32 s4, 0
	s_cbranch_scc0 .Ldiff_fin_keep
	s_waitcnt vmcnt(0)
.Ldiff_fin_keep:
	s_waitcnt vmcnt(8) lgkmcnt(0)
	s_barrier
	s_branch .LBB0_779
